# attention softmax row max taken on raw scores then scaled once (max_i fl(s*x_i) == fl(s*max_i x_i), s>0): 15 fewer VALU multiplies per softmax per key tile
# baseline (speedup 1.0000x reference)
.LBB0_1035:
	s_add_i32 s12, s13, 1
	s_bitcmp1_b32 s13, 0
	s_cselect_b32 s13, 0x4800, 0
	v_or_b32_e32 v80, s13, v42
	v_add_u32_e32 v55, v80, v47
	ds_read_b128 v[56:59], v55
	ds_read_b128 v[60:63], v55 offset:64
	v_add_u32_e32 v84, v80, v53
	ds_read_b128 v[80:83], v84 offset:9216
	s_andn2_b64 vcc, exec, s[66:67]
	s_waitcnt lgkmcnt(2)
	v_mfma_f32_16x16x32_bf16 v[56:59], v[56:59], v[2:5], 0
	ds_read_b128 v[64:67], v55 offset:640
	ds_read_b128 v[68:71], v55 offset:4672
	ds_read_b128 v[72:75], v55 offset:5248
	s_waitcnt lgkmcnt(4)
	v_mfma_f32_16x16x32_bf16 v[56:59], v[60:63], v[6:9], v[56:59]
	ds_read_b128 v[60:63], v55 offset:576
	s_waitcnt lgkmcnt(0)
	v_mfma_f32_16x16x32_bf16 v[60:63], v[60:63], v[2:5], 0
	v_mfma_f32_16x16x32_bf16 v[60:63], v[64:67], v[6:9], v[60:63]
	ds_read_b128 v[64:67], v55 offset:4608
	s_waitcnt lgkmcnt(0)
	v_mfma_f32_16x16x32_bf16 v[64:67], v[64:67], v[2:5], 0
	v_mfma_f32_16x16x32_bf16 v[64:67], v[68:71], v[6:9], v[64:67]
	ds_read_b128 v[68:71], v55 offset:5184
	s_waitcnt lgkmcnt(0)
	v_mfma_f32_16x16x32_bf16 v[68:71], v[68:71], v[2:5], 0
	v_mfma_f32_16x16x32_bf16 v[68:71], v[72:75], v[6:9], v[68:71]
	v_max_f32_e32 v55, v56, v57
	v_max3_f32 v55, v55, v58, v59
	v_max3_f32 v55, v55, v60, v61
	v_max3_f32 v55, v55, v62, v63
	v_max3_f32 v55, v55, v64, v65
	v_max3_f32 v55, v55, v66, v67
	v_max3_f32 v55, v55, v68, v69
	v_max3_f32 v55, v55, v70, v71
	v_mul_f32_e32 v55, 0x3e38aa3b, v55
	v_max_f32_e32 v55, s88, v55
	ds_bpermute_b32 v72, v43, v55
	s_waitcnt lgkmcnt(0)
	v_max_f32_e32 v72, v72, v72
	v_max_f32_e32 v55, v55, v72
	ds_bpermute_b32 v72, v1, v55
	s_waitcnt lgkmcnt(0)
	ds_read_b128 v[210:213], v84 offset:11520
	ds_read_b128 v[214:217], v84 offset:11584
	ds_read_b128 v[218:221], v84 offset:13824
	ds_read_b128 v[222:225], v84 offset:13888
	ds_read_b128 v[226:229], v84 offset:16128
	ds_read_b128 v[230:233], v84 offset:16192
	v_max3_f32 v55, v52, v55, v72
	v_sub_f32_e32 v52, v52, v55
	v_fma_f32 v56, v56, s91, -v55
	v_fma_f32 v57, v57, s91, -v55
	v_fma_f32 v58, v58, s91, -v55
	v_fma_f32 v59, v59, s91, -v55
	v_fma_f32 v60, v60, s91, -v55
	v_fma_f32 v61, v61, s91, -v55
	v_fma_f32 v62, v62, s91, -v55
	v_fma_f32 v63, v63, s91, -v55
	v_exp_f32_e32 v52, v52
	v_exp_f32_e32 v56, v56
	v_exp_f32_e32 v57, v57
	v_exp_f32_e32 v58, v58
	v_exp_f32_e32 v59, v59
	v_exp_f32_e32 v60, v60
	v_exp_f32_e32 v61, v61
	v_exp_f32_e32 v62, v62
	v_exp_f32_e32 v63, v63
	v_pk_mul_f32 v[28:29], v[28:29], v[52:53] op_sel_hi:[1,0]
	v_pk_mul_f32 v[26:27], v[26:27], v[52:53] op_sel_hi:[1,0]
	v_cvt_pk_bf16_f32 v72, v56, v57
	v_cvt_pk_bf16_f32 v73, v58, v59
	v_cvt_pk_bf16_f32 v74, v60, v61
	v_cvt_pk_bf16_f32 v75, v62, v63
	v_fma_f32 v64, v64, s91, -v55
	v_fma_f32 v65, v65, s91, -v55
	v_mfma_f32_16x16x32_bf16 v[26:29], v[80:83], v[72:75], v[26:29]
	ds_read_b128 v[80:83], v84 offset:9280
	v_fma_f32 v66, v66, s91, -v55
	v_fma_f32 v67, v67, s91, -v55
	v_fma_f32 v68, v68, s91, -v55
	v_fma_f32 v69, v69, s91, -v55
	v_fma_f32 v70, v70, s91, -v55
	v_fma_f32 v71, v71, s91, -v55
	v_exp_f32_e32 v64, v64
	v_exp_f32_e32 v65, v65
	v_exp_f32_e32 v66, v66
	v_exp_f32_e32 v67, v67
	v_exp_f32_e32 v68, v68
	v_exp_f32_e32 v69, v69
	v_exp_f32_e32 v70, v70
	v_exp_f32_e32 v71, v71
	v_cvt_pk_bf16_f32 v76, v64, v65
	v_cvt_pk_bf16_f32 v77, v66, v67
	v_cvt_pk_bf16_f32 v78, v68, v69
	v_cvt_pk_bf16_f32 v79, v70, v71
	v_pk_mul_f32 v[32:33], v[32:33], v[52:53] op_sel_hi:[1,0]
	v_pk_mul_f32 v[30:31], v[30:31], v[52:53] op_sel_hi:[1,0]
	s_waitcnt lgkmcnt(0)
	v_mfma_f32_16x16x32_bf16 v[26:29], v[80:83], v[76:79], v[26:29]
	v_pk_mul_f32 v[36:37], v[36:37], v[52:53] op_sel_hi:[1,0]
	v_pk_mul_f32 v[34:35], v[34:35], v[52:53] op_sel_hi:[1,0]
	s_waitcnt lgkmcnt(6)
	v_mfma_f32_16x16x32_bf16 v[30:33], v[210:213], v[72:75], v[30:33]
	v_pk_mul_f32 v[40:41], v[40:41], v[52:53] op_sel_hi:[1,0]
	v_pk_mul_f32 v[38:39], v[38:39], v[52:53] op_sel_hi:[1,0]
	s_waitcnt lgkmcnt(5)
	v_mfma_f32_16x16x32_bf16 v[30:33], v[214:217], v[76:79], v[30:33]
	s_waitcnt lgkmcnt(4)
	v_mfma_f32_16x16x32_bf16 v[34:37], v[218:221], v[72:75], v[34:37]
	s_waitcnt lgkmcnt(3)
	v_mfma_f32_16x16x32_bf16 v[34:37], v[222:225], v[76:79], v[34:37]
	s_waitcnt lgkmcnt(2)
	v_mfma_f32_16x16x32_bf16 v[38:41], v[226:229], v[72:75], v[38:41]
	s_waitcnt lgkmcnt(1)
	v_mfma_f32_16x16x32_bf16 v[38:41], v[230:233], v[76:79], v[38:41]
	s_cbranch_vccnz .LBB0_1037
	s_bitcmp1_b32 s12, 0
	s_cselect_b32 s13, 0x4800, 0
	v_add_u32_e32 v72, s13, v46
	s_waitcnt vmcnt(3)
	ds_write_b128 v72, v[14:17]
	s_waitcnt vmcnt(2)
	ds_write_b128 v72, v[10:13] offset:16
	s_waitcnt vmcnt(0)
	ds_write_b128 v72, v[22:25] offset:9216
	ds_write_b128 v72, v[18:21] offset:9232

.LBB0_1045:
	s_add_i32 s68, s12, 1
	s_bitcmp1_b32 s12, 0
	s_cselect_b32 s12, 0x4800, 0
	v_or_b32_e32 v99, s12, v74
	v_add_u32_e32 v93, v99, v81
	ds_read_b128 v[62:65], v93
	ds_read_b128 v[66:69], v93 offset:576
	ds_read_b128 v[70:73], v93 offset:4608
	ds_read_b128 v[88:91], v93 offset:5184
	s_andn2_b64 vcc, exec, s[66:67]
	s_waitcnt vmcnt(1) lgkmcnt(3)
	v_mfma_f32_16x16x32_bf16 v[62:65], v[62:65], v[50:53], 0
	s_waitcnt lgkmcnt(2)
	v_mfma_f32_16x16x32_bf16 v[66:69], v[66:69], v[50:53], 0
	s_nop 5
	v_max_f32_e32 v59, v62, v63
	s_waitcnt lgkmcnt(1)
	v_mfma_f32_16x16x32_bf16 v[70:73], v[70:73], v[50:53], 0
	s_waitcnt lgkmcnt(0)
	v_mfma_f32_16x16x32_bf16 v[122:125], v[88:91], v[50:53], 0
	v_max3_f32 v59, v59, v64, v65
	v_max3_f32 v59, v59, v66, v67
	v_max3_f32 v59, v59, v68, v69
	v_max3_f32 v59, v59, v70, v71
	v_max3_f32 v59, v59, v72, v73
	v_max3_f32 v59, v59, v122, v123
	v_max3_f32 v59, v59, v124, v125
	v_mul_f32_e32 v59, 0x3e8293ee, v59
	v_max_f32_e32 v59, s88, v59
	ds_bpermute_b32 v60, v75, v59
	s_waitcnt lgkmcnt(0)
	v_max_f32_e32 v60, v60, v60
	v_max_f32_e32 v59, v59, v60
	ds_bpermute_b32 v60, v1, v59
	s_waitcnt lgkmcnt(0)
	v_max3_f32 v114, v58, v59, v60
	v_fma_f32 v59, v62, s89, -v114
	v_exp_f32_e32 v115, v59
	v_fma_f32 v59, v63, s89, -v114
	v_exp_f32_e32 v116, v59
	v_fma_f32 v59, v64, s89, -v114
	v_exp_f32_e32 v117, v59
	v_fma_f32 v59, v65, s89, -v114
	v_exp_f32_e32 v118, v59
	v_fma_f32 v59, v66, s89, -v114
	v_exp_f32_e32 v119, v59
	v_fma_f32 v59, v67, s89, -v114
	v_exp_f32_e32 v120, v59
	v_fma_f32 v59, v68, s89, -v114
	v_exp_f32_e32 v96, v59
	v_fma_f32 v59, v69, s89, -v114
	v_exp_f32_e32 v110, v59
	v_fma_f32 v59, v70, s89, -v114
	v_exp_f32_e32 v94, v59
	v_fma_f32 v59, v71, s89, -v114
	ds_read_b128 v[62:65], v93 offset:64
	ds_read_b128 v[66:69], v93 offset:640
	v_exp_f32_e32 v108, v59
	v_fma_f32 v59, v72, s89, -v114
	v_exp_f32_e32 v92, v59
	v_fma_f32 v59, v73, s89, -v114
	v_exp_f32_e32 v104, v59
	v_fma_f32 v59, v122, s89, -v114
	v_exp_f32_e32 v90, v59
	v_fma_f32 v59, v123, s89, -v114
	ds_read_b128 v[70:73], v93 offset:4672
	v_exp_f32_e32 v102, v59
	v_fma_f32 v59, v124, s89, -v114
	v_exp_f32_e32 v88, v59
	v_fma_f32 v59, v125, s89, -v114
	ds_read_b128 v[122:125], v93 offset:5248
	s_waitcnt vmcnt(0) lgkmcnt(3)
	v_mfma_f32_16x16x32_bf16 v[62:65], v[62:65], v[54:57], 0
	v_sub_f32_e32 v58, v58, v114
	v_exp_f32_e32 v98, v58
	v_exp_f32_e32 v100, v59
	s_waitcnt lgkmcnt(2)
	v_mfma_f32_16x16x32_bf16 v[66:69], v[66:69], v[54:57], 0
	v_cvt_pk_bf16_f32 v58, v115, v116
	s_nop 1
	s_waitcnt lgkmcnt(1)
	v_mfma_f32_16x16x32_bf16 v[70:73], v[70:73], v[54:57], 0
	v_max_f32_e32 v89, v62, v63
	s_waitcnt lgkmcnt(0)
	v_mfma_f32_16x16x32_bf16 v[128:131], v[122:125], v[54:57], 0
	v_max3_f32 v89, v89, v64, v65
	v_max3_f32 v89, v89, v66, v67
	v_max3_f32 v89, v89, v68, v69
	v_max3_f32 v89, v89, v70, v71
	v_max3_f32 v89, v89, v72, v73
	v_max3_f32 v89, v89, v128, v129
	v_max3_f32 v89, v89, v130, v131
	v_mul_f32_e32 v89, 0x3e8293ee, v89
	v_max_f32_e32 v89, s88, v89
	ds_bpermute_b32 v91, v75, v89
	v_pk_mul_f32 v[4:5], v[4:5], v[98:99] op_sel_hi:[1,0]
	v_pk_mul_f32 v[2:3], v[2:3], v[98:99] op_sel_hi:[1,0]
	v_pk_mul_f32 v[12:13], v[12:13], v[98:99] op_sel_hi:[1,0]
	v_pk_mul_f32 v[10:11], v[10:11], v[98:99] op_sel_hi:[1,0]
	s_waitcnt lgkmcnt(0)
	v_max_f32_e32 v91, v91, v91
	v_max_f32_e32 v89, v89, v91
	ds_bpermute_b32 v91, v1, v89
	v_pk_mul_f32 v[16:17], v[16:17], v[98:99] op_sel_hi:[1,0]
	v_pk_mul_f32 v[14:15], v[14:15], v[98:99] op_sel_hi:[1,0]
	v_cvt_pk_bf16_f32 v59, v117, v118
	v_cvt_pk_bf16_f32 v60, v119, v120
	s_waitcnt lgkmcnt(0)
	v_max3_f32 v121, v61, v89, v91
	v_fma_f32 v62, v62, s89, -v121
	v_exp_f32_e32 v122, v62
	v_fma_f32 v62, v63, s89, -v121
	v_exp_f32_e32 v123, v62
	v_fma_f32 v62, v64, s89, -v121
	v_exp_f32_e32 v124, v62
	v_fma_f32 v62, v65, s89, -v121
	v_exp_f32_e32 v125, v62
	v_fma_f32 v62, v66, s89, -v121
	v_exp_f32_e32 v126, v62
	v_fma_f32 v62, v67, s89, -v121
	v_exp_f32_e32 v127, v62
	v_fma_f32 v62, v68, s89, -v121
	v_exp_f32_e32 v97, v62
	v_fma_f32 v62, v69, s89, -v121
	v_exp_f32_e32 v111, v62
	v_fma_f32 v62, v70, s89, -v121
	v_exp_f32_e32 v95, v62
	v_fma_f32 v62, v71, s89, -v121
	v_exp_f32_e32 v109, v62
	v_fma_f32 v62, v72, s89, -v121
	v_exp_f32_e32 v93, v62
	v_fma_f32 v62, v73, s89, -v121
	v_exp_f32_e32 v105, v62
	v_fma_f32 v62, v128, s89, -v121
	v_exp_f32_e32 v91, v62
	v_fma_f32 v62, v129, s89, -v121
	v_exp_f32_e32 v103, v62
	v_fma_f32 v62, v130, s89, -v121
	v_exp_f32_e32 v89, v62
	v_fma_f32 v62, v131, s89, -v121
	v_exp_f32_e32 v101, v62
	v_pk_mul_f32 v[64:65], v[20:21], v[98:99] op_sel_hi:[1,0]
	v_pk_mul_f32 v[62:63], v[18:19], v[98:99] op_sel_hi:[1,0]
	v_add_u32_e32 v99, v99, v87
	ds_read_b128 v[210:213], v99 offset:9280
	ds_read_b128 v[214:217], v99 offset:11520
	ds_read_b128 v[218:221], v99 offset:11584
	ds_read_b128 v[222:225], v99 offset:13824
	ds_read_b128 v[226:229], v99 offset:13888
	ds_read_b128 v[230:233], v99 offset:16128
	ds_read_b128 v[234:237], v99 offset:16192
	ds_read_b128 v[128:131], v99 offset:9216
	v_sub_f32_e32 v61, v61, v121
	v_exp_f32_e32 v112, v61
	v_cvt_pk_bf16_f32 v61, v96, v110
	v_cvt_pk_bf16_f32 v70, v122, v123
	v_cvt_pk_bf16_f32 v71, v124, v125
	v_pk_mul_f32 v[8:9], v[8:9], v[112:113] op_sel_hi:[1,0]
	v_pk_mul_f32 v[6:7], v[6:7], v[112:113] op_sel_hi:[1,0]
	v_cvt_pk_bf16_f32 v72, v126, v127
	v_cvt_pk_bf16_f32 v73, v97, v111
	s_waitcnt lgkmcnt(0)
	v_mfma_f32_16x16x32_bf16 v[2:5], v[128:131], v[58:61], v[2:5]
	v_cvt_pk_bf16_f32 v18, v94, v108
	v_cvt_pk_bf16_f32 v19, v92, v104
	v_cvt_pk_bf16_f32 v20, v90, v102
	v_mfma_f32_16x16x32_bf16 v[6:9], v[128:131], v[70:73], v[6:9]
	v_cvt_pk_bf16_f32 v21, v88, v100
	v_pk_mul_f32 v[68:69], v[32:33], v[112:113] op_sel_hi:[1,0]
	v_pk_mul_f32 v[66:67], v[30:31], v[112:113] op_sel_hi:[1,0]
	v_cvt_pk_bf16_f32 v30, v95, v109
	v_cvt_pk_bf16_f32 v31, v93, v105
	v_cvt_pk_bf16_f32 v32, v91, v103
	v_cvt_pk_bf16_f32 v33, v89, v101
	s_waitcnt lgkmcnt(7)
	v_mfma_f32_16x16x32_bf16 v[2:5], v[210:213], v[18:21], v[2:5]
	v_mul_f32_e64 v24, v24, v112
	v_mul_f32_e64 v25, v25, v112
	v_pk_mul_f32 v[22:23], v[22:23], v[112:113] op_sel_hi:[1,0]
	v_pk_mul_f32 v[28:29], v[28:29], v[112:113] op_sel_hi:[1,0]
	v_mfma_f32_16x16x32_bf16 v[6:9], v[210:213], v[30:33], v[6:9]
	v_pk_mul_f32 v[26:27], v[26:27], v[112:113] op_sel_hi:[1,0]
	s_waitcnt lgkmcnt(6)
	v_mfma_f32_16x16x32_bf16 v[10:13], v[214:217], v[58:61], v[10:13]
	v_mfma_f32_16x16x32_bf16 v[22:25], v[214:217], v[70:73], v[22:25]
	s_waitcnt lgkmcnt(5)
	v_mfma_f32_16x16x32_bf16 v[10:13], v[218:221], v[18:21], v[10:13]
	v_mfma_f32_16x16x32_bf16 v[22:25], v[218:221], v[30:33], v[22:25]
	s_waitcnt lgkmcnt(4)
	v_mfma_f32_16x16x32_bf16 v[14:17], v[222:225], v[58:61], v[14:17]
	v_mfma_f32_16x16x32_bf16 v[26:29], v[222:225], v[70:73], v[26:29]
	s_waitcnt lgkmcnt(3)
	v_mfma_f32_16x16x32_bf16 v[14:17], v[226:229], v[18:21], v[14:17]
	v_mfma_f32_16x16x32_bf16 v[26:29], v[226:229], v[30:33], v[26:29]
	s_waitcnt lgkmcnt(2)
	v_mfma_f32_16x16x32_bf16 v[58:61], v[230:233], v[58:61], v[62:65]
	v_mfma_f32_16x16x32_bf16 v[62:65], v[230:233], v[70:73], v[66:69]
	s_nop 2
	s_waitcnt lgkmcnt(1)
	v_mfma_f32_16x16x32_bf16 v[18:21], v[234:237], v[18:21], v[58:61]
	v_mfma_f32_16x16x32_bf16 v[30:33], v[234:237], v[30:33], v[62:65]
	s_cbranch_vccnz .LBB0_1042
	s_bitcmp1_b32 s68, 0
	s_cselect_b32 s12, 0x4800, 0
	v_add_u32_e32 v58, s12, v80
	ds_write_b128 v58, v[34:37]
	ds_write_b128 v58, v[38:41] offset:16
	ds_write_b128 v58, v[42:45] offset:9216
	ds_write_b128 v58, v[46:49] offset:9232
	s_branch .LBB0_1042

.LBB0_1076:
	s_bitcmp1_b32 s12, 0
	s_cselect_b32 s12, 0x4800, 0
	v_or_b32_e32 v99, s12, v74
	v_add_u32_e32 v93, v99, v77
	ds_read_b128 v[62:65], v93
	ds_read_b128 v[66:69], v93 offset:576
	ds_read_b128 v[70:73], v93 offset:4608
	ds_read_b128 v[88:91], v93 offset:5184
	s_andn2_b64 vcc, exec, s[66:67]
	s_waitcnt vmcnt(1) lgkmcnt(3)
	v_mfma_f32_16x16x32_bf16 v[62:65], v[62:65], v[42:45], 0
	s_waitcnt lgkmcnt(2)
	v_mfma_f32_16x16x32_bf16 v[66:69], v[66:69], v[42:45], 0
	s_nop 5
	v_max_f32_e32 v59, v62, v63
	s_waitcnt lgkmcnt(1)
	v_mfma_f32_16x16x32_bf16 v[70:73], v[70:73], v[42:45], 0
	v_max3_f32 v59, v59, v64, v65
	s_waitcnt lgkmcnt(0)
	v_mfma_f32_16x16x32_bf16 v[122:125], v[88:91], v[42:45], 0
	v_max3_f32 v59, v59, v66, v67
	v_max3_f32 v59, v59, v68, v69
	v_max3_f32 v59, v59, v70, v71
	v_max3_f32 v59, v59, v72, v73
	v_max3_f32 v59, v59, v122, v123
	v_max3_f32 v59, v59, v124, v125
	v_mul_f32_e32 v59, 0x3e8293ee, v59
	v_max_f32_e32 v59, s88, v59
	ds_bpermute_b32 v60, v114, v59
	s_waitcnt lgkmcnt(0)
	v_max_f32_e32 v60, v60, v60
	v_max_f32_e32 v59, v59, v60
	ds_bpermute_b32 v60, v75, v59
	s_waitcnt lgkmcnt(0)
	v_max3_f32 v81, v58, v59, v60
	v_fma_f32 v59, v62, s89, -v81
	v_exp_f32_e32 v115, v59
	v_fma_f32 v59, v63, s89, -v81
	v_exp_f32_e32 v116, v59
	v_fma_f32 v59, v64, s89, -v81
	v_exp_f32_e32 v117, v59
	v_fma_f32 v59, v65, s89, -v81
	v_exp_f32_e32 v118, v59
	v_fma_f32 v59, v66, s89, -v81
	v_exp_f32_e32 v119, v59
	v_fma_f32 v59, v67, s89, -v81
	v_exp_f32_e32 v120, v59
	v_fma_f32 v59, v68, s89, -v81
	v_exp_f32_e32 v96, v59
	v_fma_f32 v59, v69, s89, -v81
	v_exp_f32_e32 v110, v59
	v_fma_f32 v59, v70, s89, -v81
	v_exp_f32_e32 v94, v59
	v_fma_f32 v59, v71, s89, -v81
	ds_read_b128 v[62:65], v93 offset:64
	ds_read_b128 v[66:69], v93 offset:640
	v_exp_f32_e32 v108, v59
	v_fma_f32 v59, v72, s89, -v81
	v_exp_f32_e32 v92, v59
	v_fma_f32 v59, v73, s89, -v81
	v_exp_f32_e32 v104, v59
	v_fma_f32 v59, v122, s89, -v81
	v_exp_f32_e32 v90, v59
	v_fma_f32 v59, v123, s89, -v81
	ds_read_b128 v[70:73], v93 offset:4672
	v_exp_f32_e32 v102, v59
	v_fma_f32 v59, v124, s89, -v81
	v_exp_f32_e32 v88, v59
	v_fma_f32 v59, v125, s89, -v81
	ds_read_b128 v[122:125], v93 offset:5248
	s_waitcnt vmcnt(0) lgkmcnt(3)
	v_mfma_f32_16x16x32_bf16 v[62:65], v[62:65], v[46:49], 0
	v_sub_f32_e32 v58, v58, v81
	v_exp_f32_e32 v98, v58
	v_exp_f32_e32 v100, v59
	s_waitcnt lgkmcnt(2)
	v_mfma_f32_16x16x32_bf16 v[66:69], v[66:69], v[46:49], 0
	v_cvt_pk_bf16_f32 v58, v115, v116
	s_nop 1
	s_waitcnt lgkmcnt(1)
	v_mfma_f32_16x16x32_bf16 v[70:73], v[70:73], v[46:49], 0
	v_max_f32_e32 v89, v62, v63
	s_waitcnt lgkmcnt(0)
	v_mfma_f32_16x16x32_bf16 v[128:131], v[122:125], v[46:49], 0
	v_max3_f32 v89, v89, v64, v65
	v_max3_f32 v89, v89, v66, v67
	v_max3_f32 v89, v89, v68, v69
	v_max3_f32 v89, v89, v70, v71
	v_max3_f32 v89, v89, v72, v73
	v_max3_f32 v89, v89, v128, v129
	v_max3_f32 v89, v89, v130, v131
	v_mul_f32_e32 v89, 0x3e8293ee, v89
	v_max_f32_e32 v89, s88, v89
	ds_bpermute_b32 v91, v114, v89
	v_pk_mul_f32 v[8:9], v[8:9], v[98:99] op_sel_hi:[1,0]
	v_pk_mul_f32 v[6:7], v[6:7], v[98:99] op_sel_hi:[1,0]
	v_pk_mul_f32 v[12:13], v[12:13], v[98:99] op_sel_hi:[1,0]
	v_pk_mul_f32 v[10:11], v[10:11], v[98:99] op_sel_hi:[1,0]
	s_waitcnt lgkmcnt(0)
	v_max_f32_e32 v91, v91, v91
	v_max_f32_e32 v89, v89, v91
	ds_bpermute_b32 v91, v75, v89
	v_pk_mul_f32 v[20:21], v[20:21], v[98:99] op_sel_hi:[1,0]
	v_pk_mul_f32 v[18:19], v[18:19], v[98:99] op_sel_hi:[1,0]
	v_cvt_pk_bf16_f32 v59, v117, v118
	v_cvt_pk_bf16_f32 v60, v119, v120
	s_waitcnt lgkmcnt(0)
	v_max3_f32 v121, v61, v89, v91
	v_fma_f32 v62, v62, s89, -v121
	v_exp_f32_e32 v122, v62
	v_fma_f32 v62, v63, s89, -v121
	v_exp_f32_e32 v123, v62
	v_fma_f32 v62, v64, s89, -v121
	v_exp_f32_e32 v124, v62
	v_fma_f32 v62, v65, s89, -v121
	v_exp_f32_e32 v125, v62
	v_fma_f32 v62, v66, s89, -v121
	v_exp_f32_e32 v126, v62
	v_fma_f32 v62, v67, s89, -v121
	v_exp_f32_e32 v127, v62
	v_fma_f32 v62, v68, s89, -v121
	v_exp_f32_e32 v97, v62
	v_fma_f32 v62, v69, s89, -v121
	v_exp_f32_e32 v111, v62
	v_fma_f32 v62, v70, s89, -v121
	v_exp_f32_e32 v95, v62
	v_fma_f32 v62, v71, s89, -v121
	v_exp_f32_e32 v109, v62
	v_fma_f32 v62, v72, s89, -v121
	v_exp_f32_e32 v93, v62
	v_fma_f32 v62, v73, s89, -v121
	v_exp_f32_e32 v105, v62
	v_fma_f32 v62, v128, s89, -v121
	v_exp_f32_e32 v91, v62
	v_fma_f32 v62, v129, s89, -v121
	v_exp_f32_e32 v103, v62
	v_fma_f32 v62, v130, s89, -v121
	v_exp_f32_e32 v89, v62
	v_fma_f32 v62, v131, s89, -v121
	v_exp_f32_e32 v101, v62
	v_pk_mul_f32 v[64:65], v[24:25], v[98:99] op_sel_hi:[1,0]
	v_pk_mul_f32 v[62:63], v[22:23], v[98:99] op_sel_hi:[1,0]
	v_add_u32_e32 v99, v99, v87
	ds_read_b128 v[210:213], v99 offset:9280
	ds_read_b128 v[214:217], v99 offset:11520
	ds_read_b128 v[218:221], v99 offset:11584
	ds_read_b128 v[222:225], v99 offset:13824
	ds_read_b128 v[226:229], v99 offset:13888
	ds_read_b128 v[230:233], v99 offset:16128
	ds_read_b128 v[234:237], v99 offset:16192
	ds_read_b128 v[128:131], v99 offset:9216
	v_sub_f32_e32 v61, v61, v121
	v_exp_f32_e32 v112, v61
	v_cvt_pk_bf16_f32 v61, v96, v110
	v_cvt_pk_bf16_f32 v70, v122, v123
	v_cvt_pk_bf16_f32 v71, v124, v125
	v_pk_mul_f32 v[4:5], v[4:5], v[112:113] op_sel_hi:[1,0]
	v_pk_mul_f32 v[2:3], v[2:3], v[112:113] op_sel_hi:[1,0]
	v_cvt_pk_bf16_f32 v72, v126, v127
	v_cvt_pk_bf16_f32 v73, v97, v111
	s_waitcnt lgkmcnt(0)
	v_mfma_f32_16x16x32_bf16 v[6:9], v[128:131], v[58:61], v[6:9]
	v_cvt_pk_bf16_f32 v22, v94, v108
	v_cvt_pk_bf16_f32 v23, v92, v104
	v_cvt_pk_bf16_f32 v24, v90, v102
	v_mfma_f32_16x16x32_bf16 v[2:5], v[128:131], v[70:73], v[2:5]
	v_cvt_pk_bf16_f32 v25, v88, v100
	v_pk_mul_f32 v[68:69], v[32:33], v[112:113] op_sel_hi:[1,0]
	v_pk_mul_f32 v[66:67], v[30:31], v[112:113] op_sel_hi:[1,0]
	v_cvt_pk_bf16_f32 v30, v95, v109
	v_cvt_pk_bf16_f32 v31, v93, v105
	v_cvt_pk_bf16_f32 v32, v91, v103
	v_cvt_pk_bf16_f32 v33, v89, v101
	s_waitcnt lgkmcnt(7)
	v_mfma_f32_16x16x32_bf16 v[6:9], v[210:213], v[22:25], v[6:9]
	v_mul_f32_e64 v16, v16, v112
	v_mul_f32_e64 v17, v17, v112
	v_pk_mul_f32 v[14:15], v[14:15], v[112:113] op_sel_hi:[1,0]
	v_pk_mul_f32 v[28:29], v[28:29], v[112:113] op_sel_hi:[1,0]
	v_mfma_f32_16x16x32_bf16 v[2:5], v[210:213], v[30:33], v[2:5]
	v_pk_mul_f32 v[26:27], v[26:27], v[112:113] op_sel_hi:[1,0]
	s_waitcnt lgkmcnt(6)
	v_mfma_f32_16x16x32_bf16 v[10:13], v[214:217], v[58:61], v[10:13]
	v_mfma_f32_16x16x32_bf16 v[14:17], v[214:217], v[70:73], v[14:17]
	s_waitcnt lgkmcnt(5)
	v_mfma_f32_16x16x32_bf16 v[10:13], v[218:221], v[22:25], v[10:13]
	v_mfma_f32_16x16x32_bf16 v[14:17], v[218:221], v[30:33], v[14:17]
	s_waitcnt lgkmcnt(4)
	v_mfma_f32_16x16x32_bf16 v[18:21], v[222:225], v[58:61], v[18:21]
	v_mfma_f32_16x16x32_bf16 v[26:29], v[222:225], v[70:73], v[26:29]
	s_waitcnt lgkmcnt(3)
	v_mfma_f32_16x16x32_bf16 v[18:21], v[226:229], v[22:25], v[18:21]
	v_mfma_f32_16x16x32_bf16 v[26:29], v[226:229], v[30:33], v[26:29]
	s_waitcnt lgkmcnt(2)
	v_mfma_f32_16x16x32_bf16 v[58:61], v[230:233], v[58:61], v[62:65]
	v_mfma_f32_16x16x32_bf16 v[62:65], v[230:233], v[70:73], v[66:69]
	s_nop 2
	s_waitcnt lgkmcnt(1)
	v_mfma_f32_16x16x32_bf16 v[22:25], v[234:237], v[22:25], v[58:61]
	v_mfma_f32_16x16x32_bf16 v[30:33], v[234:237], v[30:33], v[62:65]
	s_cbranch_vccnz .LBB0_1073
	s_bitcmp1_b32 s68, 0
	s_cselect_b32 s12, 0x4800, 0
	v_add_u32_e32 v58, s12, v80
	ds_write_b128 v58, v[38:41]
	ds_write_b128 v58, v[34:37] offset:16
	ds_write_b128 v58, v[50:53] offset:9216
	ds_write_b128 v58, v[54:57] offset:9232
	s_branch .LBB0_1073

.LBB0_1163:
	s_add_i32 s12, s13, 1
	s_bitcmp1_b32 s13, 0
	s_cselect_b32 s13, 0x4800, 0
	v_or_b32_e32 v80, s13, v42
	v_add_u32_e32 v55, v80, v47
	ds_read_b128 v[56:59], v55
	ds_read_b128 v[60:63], v55 offset:64
	v_add_u32_e32 v84, v80, v53
	ds_read_b128 v[80:83], v84 offset:9216
	s_andn2_b64 vcc, exec, s[60:61]
	s_waitcnt lgkmcnt(2)
	v_mfma_f32_16x16x32_bf16 v[56:59], v[56:59], v[2:5], 0
	ds_read_b128 v[64:67], v55 offset:640
	ds_read_b128 v[68:71], v55 offset:4672
	ds_read_b128 v[72:75], v55 offset:5248
	s_waitcnt lgkmcnt(4)
	v_mfma_f32_16x16x32_bf16 v[56:59], v[60:63], v[6:9], v[56:59]
	ds_read_b128 v[60:63], v55 offset:576
	s_waitcnt lgkmcnt(0)
	v_mfma_f32_16x16x32_bf16 v[60:63], v[60:63], v[2:5], 0
	v_mfma_f32_16x16x32_bf16 v[60:63], v[64:67], v[6:9], v[60:63]
	ds_read_b128 v[64:67], v55 offset:4608
	s_waitcnt lgkmcnt(0)
	v_mfma_f32_16x16x32_bf16 v[64:67], v[64:67], v[2:5], 0
	v_mfma_f32_16x16x32_bf16 v[64:67], v[68:71], v[6:9], v[64:67]
	ds_read_b128 v[68:71], v55 offset:5184
	ds_read_b128 v[210:213], v84 offset:11520
	ds_read_b128 v[214:217], v84 offset:11584
	ds_read_b128 v[218:221], v84 offset:13824
	ds_read_b128 v[222:225], v84 offset:13888
	ds_read_b128 v[226:229], v84 offset:16128
	ds_read_b128 v[230:233], v84 offset:16192
	s_waitcnt lgkmcnt(0)
	v_mfma_f32_16x16x32_bf16 v[68:71], v[68:71], v[2:5], 0
	v_mfma_f32_16x16x32_bf16 v[68:71], v[72:75], v[6:9], v[68:71]
	v_max_f32_e32 v55, v56, v57
	v_max3_f32 v55, v55, v58, v59
	v_max3_f32 v55, v55, v60, v61
	v_max3_f32 v55, v55, v62, v63
	v_max3_f32 v55, v55, v64, v65
	v_max3_f32 v55, v55, v66, v67
	v_max3_f32 v55, v55, v68, v69
	v_max3_f32 v55, v55, v70, v71
	v_mul_f32_e32 v55, 0x3e38aa3b, v55
	v_max_f32_e32 v55, s88, v55
	v_mov_b32_e32 v252, v55
	v_mov_b32_e32 v253, v55
	s_nop 1
	v_permlane16_swap_b32_e32 v252, v253
	s_waitcnt lgkmcnt(0)
	v_max_f32_e32 v55, v252, v253
	v_mov_b32_e32 v254, v55
	v_mov_b32_e32 v255, v55
	s_nop 1
	v_permlane32_swap_b32_e32 v254, v255
	s_waitcnt lgkmcnt(0)
	v_max3_f32 v55, v52, v254, v255
	v_sub_f32_e32 v52, v52, v55
	v_fma_f32 v56, v56, s91, -v55
	v_fma_f32 v57, v57, s91, -v55
	v_fma_f32 v58, v58, s91, -v55
	v_fma_f32 v59, v59, s91, -v55
	v_fma_f32 v60, v60, s91, -v55
	v_fma_f32 v61, v61, s91, -v55
	v_fma_f32 v62, v62, s91, -v55
	v_fma_f32 v63, v63, s91, -v55
	v_exp_f32_e32 v52, v52
	v_exp_f32_e32 v56, v56
	v_exp_f32_e32 v57, v57
	v_exp_f32_e32 v58, v58
	v_exp_f32_e32 v59, v59
	v_exp_f32_e32 v60, v60
	v_exp_f32_e32 v61, v61
	v_exp_f32_e32 v62, v62
	v_exp_f32_e32 v63, v63
	v_pk_mul_f32 v[28:29], v[28:29], v[52:53] op_sel_hi:[1,0]
	v_pk_mul_f32 v[26:27], v[26:27], v[52:53] op_sel_hi:[1,0]
	v_cvt_pk_bf16_f32 v72, v56, v57
	v_cvt_pk_bf16_f32 v73, v58, v59
	v_cvt_pk_bf16_f32 v74, v60, v61
	v_cvt_pk_bf16_f32 v75, v62, v63
	v_fma_f32 v64, v64, s91, -v55
	v_fma_f32 v65, v65, s91, -v55
	v_mfma_f32_16x16x32_bf16 v[26:29], v[80:83], v[72:75], v[26:29]
	ds_read_b128 v[80:83], v84 offset:9280
	v_fma_f32 v66, v66, s91, -v55
	v_fma_f32 v67, v67, s91, -v55
	v_fma_f32 v68, v68, s91, -v55
	v_fma_f32 v69, v69, s91, -v55
	v_fma_f32 v70, v70, s91, -v55
	v_fma_f32 v71, v71, s91, -v55
	v_exp_f32_e32 v64, v64
	v_exp_f32_e32 v65, v65
	v_exp_f32_e32 v66, v66
	v_exp_f32_e32 v67, v67
	v_exp_f32_e32 v68, v68
	v_exp_f32_e32 v69, v69
	v_exp_f32_e32 v70, v70
	v_exp_f32_e32 v71, v71
	v_cvt_pk_bf16_f32 v76, v64, v65
	v_cvt_pk_bf16_f32 v77, v66, v67
	v_cvt_pk_bf16_f32 v78, v68, v69
	v_cvt_pk_bf16_f32 v79, v70, v71
	v_pk_mul_f32 v[32:33], v[32:33], v[52:53] op_sel_hi:[1,0]
	v_pk_mul_f32 v[30:31], v[30:31], v[52:53] op_sel_hi:[1,0]
	s_waitcnt lgkmcnt(0)
	v_mfma_f32_16x16x32_bf16 v[26:29], v[80:83], v[76:79], v[26:29]
	v_pk_mul_f32 v[36:37], v[36:37], v[52:53] op_sel_hi:[1,0]
	v_pk_mul_f32 v[34:35], v[34:35], v[52:53] op_sel_hi:[1,0]
	s_waitcnt lgkmcnt(6)
	v_mfma_f32_16x16x32_bf16 v[30:33], v[210:213], v[72:75], v[30:33]
	v_pk_mul_f32 v[40:41], v[40:41], v[52:53] op_sel_hi:[1,0]
	v_pk_mul_f32 v[38:39], v[38:39], v[52:53] op_sel_hi:[1,0]
	s_waitcnt lgkmcnt(5)
	v_mfma_f32_16x16x32_bf16 v[30:33], v[214:217], v[76:79], v[30:33]
	s_waitcnt lgkmcnt(4)
	v_mfma_f32_16x16x32_bf16 v[34:37], v[218:221], v[72:75], v[34:37]
	s_waitcnt lgkmcnt(3)
	v_mfma_f32_16x16x32_bf16 v[34:37], v[222:225], v[76:79], v[34:37]
	s_waitcnt lgkmcnt(2)
	v_mfma_f32_16x16x32_bf16 v[38:41], v[226:229], v[72:75], v[38:41]
	s_waitcnt lgkmcnt(1)
	v_mfma_f32_16x16x32_bf16 v[38:41], v[230:233], v[76:79], v[38:41]
	s_cbranch_vccnz .LBB0_1165
	s_bitcmp1_b32 s12, 0
	s_cselect_b32 s13, 0x4800, 0
	v_add_u32_e32 v72, s13, v46
	s_waitcnt vmcnt(3)
	ds_write_b128 v72, v[14:17]
	s_waitcnt vmcnt(2)
	ds_write_b128 v72, v[10:13] offset:16
	s_waitcnt vmcnt(0)
	ds_write_b128 v72, v[22:25] offset:9216
	ds_write_b128 v72, v[18:21] offset:9232

.LBB0_1173:
	s_add_i32 s68, s12, 1
	s_bitcmp1_b32 s12, 0
	s_cselect_b32 s12, 0x4800, 0
	v_or_b32_e32 v99, s12, v74
	v_add_u32_e32 v93, v99, v81
	ds_read_b128 v[62:65], v93
	ds_read_b128 v[66:69], v93 offset:576
	ds_read_b128 v[70:73], v93 offset:4608
	ds_read_b128 v[88:91], v93 offset:5184
	s_andn2_b64 vcc, exec, s[60:61]
	s_waitcnt vmcnt(1) lgkmcnt(3)
	v_mfma_f32_16x16x32_bf16 v[62:65], v[62:65], v[50:53], 0
	s_waitcnt lgkmcnt(2)
	v_mfma_f32_16x16x32_bf16 v[66:69], v[66:69], v[50:53], 0
	s_nop 5
	v_max_f32_e32 v59, v62, v63
	s_waitcnt lgkmcnt(1)
	v_mfma_f32_16x16x32_bf16 v[70:73], v[70:73], v[50:53], 0
	s_waitcnt lgkmcnt(0)
	v_mfma_f32_16x16x32_bf16 v[122:125], v[88:91], v[50:53], 0
	v_max3_f32 v59, v59, v64, v65
	v_max3_f32 v59, v59, v66, v67
	v_max3_f32 v59, v59, v68, v69
	v_max3_f32 v59, v59, v70, v71
	v_max3_f32 v59, v59, v72, v73
	v_max3_f32 v59, v59, v122, v123
	v_max3_f32 v59, v59, v124, v125
	v_mul_f32_e32 v59, 0x3e8293ee, v59
	v_max_f32_e32 v59, s88, v59
	v_mov_b32_e32 v252, v59
	v_mov_b32_e32 v253, v59
	s_nop 1
	v_permlane16_swap_b32_e32 v252, v253
	s_waitcnt lgkmcnt(0)
	v_max_f32_e32 v59, v252, v253
	v_mov_b32_e32 v254, v59
	v_mov_b32_e32 v255, v59
	s_nop 1
	v_permlane32_swap_b32_e32 v254, v255
	s_waitcnt lgkmcnt(0)
	v_max3_f32 v114, v58, v254, v255
	v_fma_f32 v59, v62, s89, -v114
	v_exp_f32_e32 v115, v59
	v_fma_f32 v59, v63, s89, -v114
	v_exp_f32_e32 v116, v59
	v_fma_f32 v59, v64, s89, -v114
	v_exp_f32_e32 v117, v59
	v_fma_f32 v59, v65, s89, -v114
	v_exp_f32_e32 v118, v59
	v_fma_f32 v59, v66, s89, -v114
	v_exp_f32_e32 v119, v59
	v_fma_f32 v59, v67, s89, -v114
	v_exp_f32_e32 v120, v59
	v_fma_f32 v59, v68, s89, -v114
	v_exp_f32_e32 v96, v59
	v_fma_f32 v59, v69, s89, -v114
	v_exp_f32_e32 v110, v59
	v_fma_f32 v59, v70, s89, -v114
	v_exp_f32_e32 v94, v59
	v_fma_f32 v59, v71, s89, -v114
	ds_read_b128 v[62:65], v93 offset:64
	ds_read_b128 v[66:69], v93 offset:640
	v_exp_f32_e32 v108, v59
	v_fma_f32 v59, v72, s89, -v114
	v_exp_f32_e32 v92, v59
	v_fma_f32 v59, v73, s89, -v114
	v_exp_f32_e32 v104, v59
	v_fma_f32 v59, v122, s89, -v114
	v_exp_f32_e32 v90, v59
	v_fma_f32 v59, v123, s89, -v114
	ds_read_b128 v[70:73], v93 offset:4672
	v_exp_f32_e32 v102, v59
	v_fma_f32 v59, v124, s89, -v114
	v_exp_f32_e32 v88, v59
	v_fma_f32 v59, v125, s89, -v114
	ds_read_b128 v[122:125], v93 offset:5248
	s_waitcnt vmcnt(0) lgkmcnt(3)
	v_mfma_f32_16x16x32_bf16 v[62:65], v[62:65], v[54:57], 0
	v_sub_f32_e32 v58, v58, v114
	v_exp_f32_e32 v98, v58
	v_exp_f32_e32 v100, v59
	s_waitcnt lgkmcnt(2)
	v_mfma_f32_16x16x32_bf16 v[66:69], v[66:69], v[54:57], 0
	v_cvt_pk_bf16_f32 v58, v115, v116
	s_nop 1
	s_waitcnt lgkmcnt(1)
	v_mfma_f32_16x16x32_bf16 v[70:73], v[70:73], v[54:57], 0
	v_max_f32_e32 v89, v62, v63
	s_waitcnt lgkmcnt(0)
	v_mfma_f32_16x16x32_bf16 v[128:131], v[122:125], v[54:57], 0
	v_max3_f32 v89, v89, v64, v65
	v_max3_f32 v89, v89, v66, v67
	v_max3_f32 v89, v89, v68, v69
	v_max3_f32 v89, v89, v70, v71
	v_max3_f32 v89, v89, v72, v73
	v_max3_f32 v89, v89, v128, v129
	v_max3_f32 v89, v89, v130, v131
	v_mul_f32_e32 v89, 0x3e8293ee, v89
	v_max_f32_e32 v89, s88, v89
	v_mov_b32_e32 v252, v89
	v_mov_b32_e32 v253, v89
	s_nop 1
	v_permlane16_swap_b32_e32 v252, v253
	v_pk_mul_f32 v[4:5], v[4:5], v[98:99] op_sel_hi:[1,0]
	v_pk_mul_f32 v[2:3], v[2:3], v[98:99] op_sel_hi:[1,0]
	v_pk_mul_f32 v[12:13], v[12:13], v[98:99] op_sel_hi:[1,0]
	v_pk_mul_f32 v[10:11], v[10:11], v[98:99] op_sel_hi:[1,0]
	s_waitcnt lgkmcnt(0)
	v_max_f32_e32 v89, v252, v253
	v_mov_b32_e32 v254, v89
	v_mov_b32_e32 v255, v89
	s_nop 1
	v_permlane32_swap_b32_e32 v254, v255
	v_pk_mul_f32 v[16:17], v[16:17], v[98:99] op_sel_hi:[1,0]
	v_pk_mul_f32 v[14:15], v[14:15], v[98:99] op_sel_hi:[1,0]
	v_cvt_pk_bf16_f32 v59, v117, v118
	v_cvt_pk_bf16_f32 v60, v119, v120
	s_waitcnt lgkmcnt(0)
	v_max3_f32 v121, v61, v254, v255
	v_fma_f32 v62, v62, s89, -v121
	v_exp_f32_e32 v122, v62
	v_fma_f32 v62, v63, s89, -v121
	v_exp_f32_e32 v123, v62
	v_fma_f32 v62, v64, s89, -v121
	v_exp_f32_e32 v124, v62
	v_fma_f32 v62, v65, s89, -v121
	v_exp_f32_e32 v125, v62
	v_fma_f32 v62, v66, s89, -v121
	v_exp_f32_e32 v126, v62
	v_fma_f32 v62, v67, s89, -v121
	v_exp_f32_e32 v127, v62
	v_fma_f32 v62, v68, s89, -v121
	v_exp_f32_e32 v97, v62
	v_fma_f32 v62, v69, s89, -v121
	v_exp_f32_e32 v111, v62
	v_fma_f32 v62, v70, s89, -v121
	v_exp_f32_e32 v95, v62
	v_fma_f32 v62, v71, s89, -v121
	v_exp_f32_e32 v109, v62
	v_fma_f32 v62, v72, s89, -v121
	v_exp_f32_e32 v93, v62
	v_fma_f32 v62, v73, s89, -v121
	v_exp_f32_e32 v105, v62
	v_fma_f32 v62, v128, s89, -v121
	v_exp_f32_e32 v91, v62
	v_fma_f32 v62, v129, s89, -v121
	v_exp_f32_e32 v103, v62
	v_fma_f32 v62, v130, s89, -v121
	v_exp_f32_e32 v89, v62
	v_fma_f32 v62, v131, s89, -v121
	v_exp_f32_e32 v101, v62
	v_pk_mul_f32 v[64:65], v[20:21], v[98:99] op_sel_hi:[1,0]
	v_pk_mul_f32 v[62:63], v[18:19], v[98:99] op_sel_hi:[1,0]
	v_add_u32_e32 v99, v99, v87
	ds_read_b128 v[210:213], v99 offset:9280
	ds_read_b128 v[214:217], v99 offset:11520
	ds_read_b128 v[218:221], v99 offset:11584
	ds_read_b128 v[222:225], v99 offset:13824
	ds_read_b128 v[226:229], v99 offset:13888
	ds_read_b128 v[230:233], v99 offset:16128
	ds_read_b128 v[234:237], v99 offset:16192
	ds_read_b128 v[128:131], v99 offset:9216
	v_sub_f32_e32 v61, v61, v121
	v_exp_f32_e32 v112, v61
	v_cvt_pk_bf16_f32 v61, v96, v110
	v_cvt_pk_bf16_f32 v70, v122, v123
	v_cvt_pk_bf16_f32 v71, v124, v125
	v_pk_mul_f32 v[8:9], v[8:9], v[112:113] op_sel_hi:[1,0]
	v_pk_mul_f32 v[6:7], v[6:7], v[112:113] op_sel_hi:[1,0]
	v_cvt_pk_bf16_f32 v72, v126, v127
	v_cvt_pk_bf16_f32 v73, v97, v111
	s_waitcnt lgkmcnt(0)
	v_mfma_f32_16x16x32_bf16 v[2:5], v[128:131], v[58:61], v[2:5]
	v_cvt_pk_bf16_f32 v18, v94, v108
	v_cvt_pk_bf16_f32 v19, v92, v104
	v_cvt_pk_bf16_f32 v20, v90, v102
	v_mfma_f32_16x16x32_bf16 v[6:9], v[128:131], v[70:73], v[6:9]
	v_cvt_pk_bf16_f32 v21, v88, v100
	v_pk_mul_f32 v[68:69], v[32:33], v[112:113] op_sel_hi:[1,0]
	v_pk_mul_f32 v[66:67], v[30:31], v[112:113] op_sel_hi:[1,0]
	v_cvt_pk_bf16_f32 v30, v95, v109
	v_cvt_pk_bf16_f32 v31, v93, v105
	v_cvt_pk_bf16_f32 v32, v91, v103
	v_cvt_pk_bf16_f32 v33, v89, v101
	s_waitcnt lgkmcnt(7)
	v_mfma_f32_16x16x32_bf16 v[2:5], v[210:213], v[18:21], v[2:5]
	v_mul_f32_e64 v24, v24, v112
	v_mul_f32_e64 v25, v25, v112
	v_pk_mul_f32 v[22:23], v[22:23], v[112:113] op_sel_hi:[1,0]
	v_pk_mul_f32 v[28:29], v[28:29], v[112:113] op_sel_hi:[1,0]
	v_mfma_f32_16x16x32_bf16 v[6:9], v[210:213], v[30:33], v[6:9]
	v_pk_mul_f32 v[26:27], v[26:27], v[112:113] op_sel_hi:[1,0]
	s_waitcnt lgkmcnt(6)
	v_mfma_f32_16x16x32_bf16 v[10:13], v[214:217], v[58:61], v[10:13]
	v_mfma_f32_16x16x32_bf16 v[22:25], v[214:217], v[70:73], v[22:25]
	s_waitcnt lgkmcnt(5)
	v_mfma_f32_16x16x32_bf16 v[10:13], v[218:221], v[18:21], v[10:13]
	v_mfma_f32_16x16x32_bf16 v[22:25], v[218:221], v[30:33], v[22:25]
	s_waitcnt lgkmcnt(4)
	v_mfma_f32_16x16x32_bf16 v[14:17], v[222:225], v[58:61], v[14:17]
	v_mfma_f32_16x16x32_bf16 v[26:29], v[222:225], v[70:73], v[26:29]
	s_waitcnt lgkmcnt(3)
	v_mfma_f32_16x16x32_bf16 v[14:17], v[226:229], v[18:21], v[14:17]
	v_mfma_f32_16x16x32_bf16 v[26:29], v[226:229], v[30:33], v[26:29]
	s_waitcnt lgkmcnt(2)
	v_mfma_f32_16x16x32_bf16 v[58:61], v[230:233], v[58:61], v[62:65]
	v_mfma_f32_16x16x32_bf16 v[62:65], v[230:233], v[70:73], v[66:69]
	s_nop 2
	s_waitcnt lgkmcnt(1)
	v_mfma_f32_16x16x32_bf16 v[18:21], v[234:237], v[18:21], v[58:61]
	v_mfma_f32_16x16x32_bf16 v[30:33], v[234:237], v[30:33], v[62:65]
	s_cbranch_vccnz .LBB0_1170
	s_bitcmp1_b32 s68, 0
	s_cselect_b32 s12, 0x4800, 0
	v_add_u32_e32 v58, s12, v80
	ds_write_b128 v58, v[34:37]
	ds_write_b128 v58, v[38:41] offset:16
	ds_write_b128 v58, v[42:45] offset:9216
	ds_write_b128 v58, v[46:49] offset:9232
	s_branch .LBB0_1170

.LBB0_1205:
	s_bitcmp1_b32 s12, 0
	s_cselect_b32 s12, 0x4800, 0
	v_or_b32_e32 v99, s12, v74
	v_add_u32_e32 v93, v99, v77
	ds_read_b128 v[62:65], v93
	ds_read_b128 v[66:69], v93 offset:576
	ds_read_b128 v[70:73], v93 offset:4608
	ds_read_b128 v[88:91], v93 offset:5184
	s_andn2_b64 vcc, exec, s[60:61]
	s_waitcnt vmcnt(1) lgkmcnt(3)
	v_mfma_f32_16x16x32_bf16 v[62:65], v[62:65], v[34:37], 0
	s_waitcnt lgkmcnt(2)
	v_mfma_f32_16x16x32_bf16 v[66:69], v[66:69], v[34:37], 0
	s_nop 5
	v_max_f32_e32 v59, v62, v63
	s_waitcnt lgkmcnt(1)
	v_mfma_f32_16x16x32_bf16 v[70:73], v[70:73], v[34:37], 0
	v_max3_f32 v59, v59, v64, v65
	s_waitcnt lgkmcnt(0)
	v_mfma_f32_16x16x32_bf16 v[122:125], v[88:91], v[34:37], 0
	v_max3_f32 v59, v59, v66, v67
	v_max3_f32 v59, v59, v68, v69
	v_max3_f32 v59, v59, v70, v71
	v_max3_f32 v59, v59, v72, v73
	v_max3_f32 v59, v59, v122, v123
	v_max3_f32 v59, v59, v124, v125
	v_mul_f32_e32 v59, 0x3e8293ee, v59
	v_max_f32_e32 v59, s88, v59
	v_mov_b32_e32 v252, v59
	v_mov_b32_e32 v253, v59
	s_nop 1
	v_permlane16_swap_b32_e32 v252, v253
	s_waitcnt lgkmcnt(0)
	v_max_f32_e32 v59, v252, v253
	v_mov_b32_e32 v254, v59
	v_mov_b32_e32 v255, v59
	s_nop 1
	v_permlane32_swap_b32_e32 v254, v255
	s_waitcnt lgkmcnt(0)
	v_max3_f32 v81, v58, v254, v255
	v_fma_f32 v59, v62, s89, -v81
	v_exp_f32_e32 v115, v59
	v_fma_f32 v59, v63, s89, -v81
	v_exp_f32_e32 v116, v59
	v_fma_f32 v59, v64, s89, -v81
	v_exp_f32_e32 v117, v59
	v_fma_f32 v59, v65, s89, -v81
	v_exp_f32_e32 v118, v59
	v_fma_f32 v59, v66, s89, -v81
	v_exp_f32_e32 v119, v59
	v_fma_f32 v59, v67, s89, -v81
	v_exp_f32_e32 v120, v59
	v_fma_f32 v59, v68, s89, -v81
	v_exp_f32_e32 v96, v59
	v_fma_f32 v59, v69, s89, -v81
	v_exp_f32_e32 v110, v59
	v_fma_f32 v59, v70, s89, -v81
	v_exp_f32_e32 v94, v59
	v_fma_f32 v59, v71, s89, -v81
	ds_read_b128 v[62:65], v93 offset:64
	ds_read_b128 v[66:69], v93 offset:640
	v_exp_f32_e32 v108, v59
	v_fma_f32 v59, v72, s89, -v81
	v_exp_f32_e32 v92, v59
	v_fma_f32 v59, v73, s89, -v81
	v_exp_f32_e32 v104, v59
	v_fma_f32 v59, v122, s89, -v81
	v_exp_f32_e32 v90, v59
	v_fma_f32 v59, v123, s89, -v81
	ds_read_b128 v[70:73], v93 offset:4672
	v_exp_f32_e32 v102, v59
	v_fma_f32 v59, v124, s89, -v81
	v_exp_f32_e32 v88, v59
	v_fma_f32 v59, v125, s89, -v81
	ds_read_b128 v[122:125], v93 offset:5248
	s_waitcnt vmcnt(0) lgkmcnt(3)
	v_mfma_f32_16x16x32_bf16 v[62:65], v[62:65], v[42:45], 0
	v_sub_f32_e32 v58, v58, v81
	v_exp_f32_e32 v98, v58
	v_exp_f32_e32 v100, v59
	s_waitcnt lgkmcnt(2)
	v_mfma_f32_16x16x32_bf16 v[66:69], v[66:69], v[42:45], 0
	v_cvt_pk_bf16_f32 v58, v115, v116
	s_nop 1
	s_waitcnt lgkmcnt(1)
	v_mfma_f32_16x16x32_bf16 v[70:73], v[70:73], v[42:45], 0
	v_max_f32_e32 v89, v62, v63
	s_waitcnt lgkmcnt(0)
	v_mfma_f32_16x16x32_bf16 v[128:131], v[122:125], v[42:45], 0
	v_max3_f32 v89, v89, v64, v65
	v_max3_f32 v89, v89, v66, v67
	v_max3_f32 v89, v89, v68, v69
	v_max3_f32 v89, v89, v70, v71
	v_max3_f32 v89, v89, v72, v73
	v_max3_f32 v89, v89, v128, v129
	v_max3_f32 v89, v89, v130, v131
	v_mul_f32_e32 v89, 0x3e8293ee, v89
	v_max_f32_e32 v89, s88, v89
	v_mov_b32_e32 v252, v89
	v_mov_b32_e32 v253, v89
	s_nop 1
	v_permlane16_swap_b32_e32 v252, v253
	v_pk_mul_f32 v[8:9], v[8:9], v[98:99] op_sel_hi:[1,0]
	v_pk_mul_f32 v[6:7], v[6:7], v[98:99] op_sel_hi:[1,0]
	v_pk_mul_f32 v[12:13], v[12:13], v[98:99] op_sel_hi:[1,0]
	v_pk_mul_f32 v[10:11], v[10:11], v[98:99] op_sel_hi:[1,0]
	s_waitcnt lgkmcnt(0)
	v_max_f32_e32 v89, v252, v253
	v_mov_b32_e32 v254, v89
	v_mov_b32_e32 v255, v89
	s_nop 1
	v_permlane32_swap_b32_e32 v254, v255
	v_pk_mul_f32 v[20:21], v[20:21], v[98:99] op_sel_hi:[1,0]
	v_pk_mul_f32 v[18:19], v[18:19], v[98:99] op_sel_hi:[1,0]
	v_cvt_pk_bf16_f32 v59, v117, v118
	v_cvt_pk_bf16_f32 v60, v119, v120
	s_waitcnt lgkmcnt(0)
	v_max3_f32 v121, v61, v254, v255
	v_fma_f32 v62, v62, s89, -v121
	v_exp_f32_e32 v122, v62
	v_fma_f32 v62, v63, s89, -v121
	v_exp_f32_e32 v123, v62
	v_fma_f32 v62, v64, s89, -v121
	v_exp_f32_e32 v124, v62
	v_fma_f32 v62, v65, s89, -v121
	v_exp_f32_e32 v125, v62
	v_fma_f32 v62, v66, s89, -v121
	v_exp_f32_e32 v126, v62
	v_fma_f32 v62, v67, s89, -v121
	v_exp_f32_e32 v127, v62
	v_fma_f32 v62, v68, s89, -v121
	v_exp_f32_e32 v97, v62
	v_fma_f32 v62, v69, s89, -v121
	v_exp_f32_e32 v111, v62
	v_fma_f32 v62, v70, s89, -v121
	v_exp_f32_e32 v95, v62
	v_fma_f32 v62, v71, s89, -v121
	v_exp_f32_e32 v109, v62
	v_fma_f32 v62, v72, s89, -v121
	v_exp_f32_e32 v93, v62
	v_fma_f32 v62, v73, s89, -v121
	v_exp_f32_e32 v105, v62
	v_fma_f32 v62, v128, s89, -v121
	v_exp_f32_e32 v91, v62
	v_fma_f32 v62, v129, s89, -v121
	v_exp_f32_e32 v103, v62
	v_fma_f32 v62, v130, s89, -v121
	v_exp_f32_e32 v89, v62
	v_fma_f32 v62, v131, s89, -v121
	v_exp_f32_e32 v101, v62
	v_pk_mul_f32 v[64:65], v[28:29], v[98:99] op_sel_hi:[1,0]
	v_pk_mul_f32 v[62:63], v[26:27], v[98:99] op_sel_hi:[1,0]
	v_add_u32_e32 v99, v99, v87
	ds_read_b128 v[210:213], v99 offset:9280
	ds_read_b128 v[214:217], v99 offset:11520
	ds_read_b128 v[218:221], v99 offset:11584
	ds_read_b128 v[222:225], v99 offset:13824
	ds_read_b128 v[226:229], v99 offset:13888
	ds_read_b128 v[230:233], v99 offset:16128
	ds_read_b128 v[234:237], v99 offset:16192
	ds_read_b128 v[128:131], v99 offset:9216
	v_sub_f32_e32 v61, v61, v121
	v_exp_f32_e32 v112, v61
	v_cvt_pk_bf16_f32 v61, v96, v110
	v_cvt_pk_bf16_f32 v70, v122, v123
	v_cvt_pk_bf16_f32 v71, v124, v125
	v_pk_mul_f32 v[4:5], v[4:5], v[112:113] op_sel_hi:[1,0]
	v_pk_mul_f32 v[2:3], v[2:3], v[112:113] op_sel_hi:[1,0]
	v_cvt_pk_bf16_f32 v72, v126, v127
	v_cvt_pk_bf16_f32 v73, v97, v111
	s_waitcnt lgkmcnt(0)
	v_mfma_f32_16x16x32_bf16 v[6:9], v[128:131], v[58:61], v[6:9]
	v_cvt_pk_bf16_f32 v26, v94, v108
	v_cvt_pk_bf16_f32 v27, v92, v104
	v_cvt_pk_bf16_f32 v28, v90, v102
	v_mfma_f32_16x16x32_bf16 v[2:5], v[128:131], v[70:73], v[2:5]
	v_cvt_pk_bf16_f32 v29, v88, v100
	v_pk_mul_f32 v[68:69], v[32:33], v[112:113] op_sel_hi:[1,0]
	v_pk_mul_f32 v[66:67], v[30:31], v[112:113] op_sel_hi:[1,0]
	v_cvt_pk_bf16_f32 v30, v95, v109
	v_cvt_pk_bf16_f32 v31, v93, v105
	v_cvt_pk_bf16_f32 v32, v91, v103
	v_cvt_pk_bf16_f32 v33, v89, v101
	s_waitcnt lgkmcnt(7)
	v_mfma_f32_16x16x32_bf16 v[6:9], v[210:213], v[26:29], v[6:9]
	v_mul_f32_e64 v16, v16, v112
	v_mul_f32_e64 v17, v17, v112
	v_pk_mul_f32 v[14:15], v[14:15], v[112:113] op_sel_hi:[1,0]
	v_pk_mul_f32 v[24:25], v[24:25], v[112:113] op_sel_hi:[1,0]
	v_mfma_f32_16x16x32_bf16 v[2:5], v[210:213], v[30:33], v[2:5]
	v_pk_mul_f32 v[22:23], v[22:23], v[112:113] op_sel_hi:[1,0]
	s_waitcnt lgkmcnt(6)
	v_mfma_f32_16x16x32_bf16 v[10:13], v[214:217], v[58:61], v[10:13]
	v_mfma_f32_16x16x32_bf16 v[14:17], v[214:217], v[70:73], v[14:17]
	s_waitcnt lgkmcnt(5)
	v_mfma_f32_16x16x32_bf16 v[10:13], v[218:221], v[26:29], v[10:13]
	v_mfma_f32_16x16x32_bf16 v[14:17], v[218:221], v[30:33], v[14:17]
	s_waitcnt lgkmcnt(4)
	v_mfma_f32_16x16x32_bf16 v[18:21], v[222:225], v[58:61], v[18:21]
	v_mfma_f32_16x16x32_bf16 v[22:25], v[222:225], v[70:73], v[22:25]
	s_waitcnt lgkmcnt(3)
	v_mfma_f32_16x16x32_bf16 v[18:21], v[226:229], v[26:29], v[18:21]
	v_mfma_f32_16x16x32_bf16 v[22:25], v[226:229], v[30:33], v[22:25]
	s_waitcnt lgkmcnt(2)
	v_mfma_f32_16x16x32_bf16 v[58:61], v[230:233], v[58:61], v[62:65]
	v_mfma_f32_16x16x32_bf16 v[62:65], v[230:233], v[70:73], v[66:69]
	s_nop 2
	s_waitcnt lgkmcnt(1)
	v_mfma_f32_16x16x32_bf16 v[26:29], v[234:237], v[26:29], v[58:61]
	v_mfma_f32_16x16x32_bf16 v[30:33], v[234:237], v[30:33], v[62:65]
	s_cbranch_vccnz .LBB0_1202
	s_bitcmp1_b32 s68, 0
	s_cselect_b32 s12, 0x4800, 0
	v_add_u32_e32 v58, s12, v80
	ds_write_b128 v58, v[46:49]
	ds_write_b128 v58, v[38:41] offset:16
	ds_write_b128 v58, v[54:57] offset:9216
	ds_write_b128 v58, v[50:53] offset:9232
	s_branch .LBB0_1202
